# P2 attention epilogue: silu-gate row loads moved to the very top of the epilogue (address rebuilt from prologue registers), ahead of the row-sum / sum-of-squares exchange
# speedup vs baseline: 1.0052x; 1.0052x over previous
.LBB0_265:
	v_lshlrev_b64 v[156:157], 1, v[184:185]
	v_lshl_add_u64 v[158:159], s[72:73], 0, v[188:189]
	v_lshl_add_u64 v[158:159], v[158:159], 0, v[156:157]
	v_lshlrev_b32_e32 v156, 1, v186
	v_mov_b32_e32 v157, 0
	v_lshl_add_u64 v[158:159], v[158:159], 0, v[156:157]
	v_lshl_add_u64 v[156:157], v[158:159], 0, s[6:7]
	v_lshl_add_u64 v[158:159], v[158:159], 0, s[12:13]
	global_load_dwordx4 v[124:127], v[156:157], off
	global_load_dwordx4 v[128:131], v[156:157], off offset:32
	global_load_dwordx4 v[132:135], v[156:157], off offset:64
	global_load_dwordx4 v[136:139], v[156:157], off offset:96
	global_load_dwordx4 v[140:143], v[158:159], off
	global_load_dwordx4 v[144:147], v[158:159], off offset:32
	global_load_dwordx4 v[148:151], v[158:159], off offset:64
	global_load_dwordx4 v[152:155], v[158:159], off offset:96
	v_mov_b32_e32 v64, v202
	s_nop 1
	v_permlane32_swap_b32_e32 v202, v64
	v_add_f32_e32 v64, v202, v64
	v_div_scale_f32 v65, s[8:9], v64, v64, 1.0
	v_rcp_f32_e32 v66, v65
	v_lshlrev_b32_e32 v67, 2, v184
	v_lshlrev_b32_e32 v68, 2, v200
	v_add3_u32 v72, 0, v67, v68
	v_fma_f32 v67, -v65, v66, 1.0
	v_fmac_f32_e32 v66, v67, v66
	v_div_scale_f32 v67, vcc, 1.0, v64, 1.0
	v_mul_f32_e32 v68, v67, v66
	v_fma_f32 v69, -v65, v68, v67
	v_fmac_f32_e32 v68, v69, v66
	v_fma_f32 v65, -v65, v68, v67
	v_div_fmas_f32 v65, v65, v66, v68
	v_div_fixup_f32 v74, v65, v64, 1.0
	v_pk_mul_f32 v[70:71], v[48:49], v[74:75] op_sel_hi:[1,0]
	v_pk_mul_f32 v[68:69], v[50:51], v[74:75] op_sel_hi:[1,0]
	v_mul_f32_e32 v50, v71, v71
	v_fmac_f32_e32 v50, v70, v70
	v_fmac_f32_e32 v50, v68, v68
	v_pk_mul_f32 v[66:67], v[52:53], v[74:75] op_sel_hi:[1,0]
	v_fmac_f32_e32 v50, v69, v69
	v_fmac_f32_e32 v50, v66, v66
	v_pk_mul_f32 v[64:65], v[54:55], v[74:75] op_sel_hi:[1,0]
	v_fmac_f32_e32 v50, v67, v67
	v_fmac_f32_e32 v50, v64, v64
	v_pk_mul_f32 v[56:57], v[56:57], v[74:75] op_sel_hi:[1,0]
	v_fmac_f32_e32 v50, v65, v65
	v_fmac_f32_e32 v50, v56, v56
	v_pk_mul_f32 v[58:59], v[58:59], v[74:75] op_sel_hi:[1,0]
	v_fmac_f32_e32 v50, v57, v57
	v_fmac_f32_e32 v50, v58, v58
	v_pk_mul_f32 v[60:61], v[60:61], v[74:75] op_sel_hi:[1,0]
	v_fmac_f32_e32 v50, v59, v59
	v_fmac_f32_e32 v50, v60, v60
	v_pk_mul_f32 v[62:63], v[62:63], v[74:75] op_sel_hi:[1,0]
	v_fmac_f32_e32 v50, v61, v61
	v_fmac_f32_e32 v50, v62, v62
	v_fmac_f32_e32 v50, v63, v63
	v_pk_mul_f32 v[54:55], v[32:33], v[74:75] op_sel_hi:[1,0]
	v_pk_mul_f32 v[52:53], v[34:35], v[74:75] op_sel_hi:[1,0]
	v_fmac_f32_e32 v50, v54, v54
	v_fmac_f32_e32 v50, v55, v55
	v_fmac_f32_e32 v50, v52, v52
	v_pk_mul_f32 v[48:49], v[36:37], v[74:75] op_sel_hi:[1,0]
	v_fmac_f32_e32 v50, v53, v53
	v_fmac_f32_e32 v50, v48, v48
	v_pk_mul_f32 v[38:39], v[38:39], v[74:75] op_sel_hi:[1,0]
	v_fmac_f32_e32 v50, v49, v49
	v_fmac_f32_e32 v50, v38, v38
	v_pk_mul_f32 v[40:41], v[40:41], v[74:75] op_sel_hi:[1,0]
	v_fmac_f32_e32 v50, v39, v39
	v_fmac_f32_e32 v50, v40, v40
	v_pk_mul_f32 v[42:43], v[42:43], v[74:75] op_sel_hi:[1,0]
	v_fmac_f32_e32 v50, v41, v41
	v_fmac_f32_e32 v50, v42, v42
	v_pk_mul_f32 v[44:45], v[44:45], v[74:75] op_sel_hi:[1,0]
	v_fmac_f32_e32 v50, v43, v43
	v_fmac_f32_e32 v50, v44, v44
	v_pk_mul_f32 v[46:47], v[46:47], v[74:75] op_sel_hi:[1,0]
	v_fmac_f32_e32 v50, v45, v45
	v_fmac_f32_e32 v50, v46, v46
	v_fmac_f32_e32 v50, v47, v47
	v_mov_b32_e32 v32, v50
	s_nop 1
	v_permlane32_swap_b32_e32 v50, v32
	s_and_saveexec_b64 s[42:43], s[0:1]
	v_add_f32_e32 v32, v50, v32
	ds_write_b32 v72, v32
	s_or_b64 exec, exec, s[42:43]
	v_mov_b32_e32 v32, v181
	s_nop 1
	v_permlane32_swap_b32_e32 v181, v32
	v_add_f32_e32 v32, v181, v32
	v_div_scale_f32 v33, s[8:9], v32, v32, 1.0
	v_rcp_f32_e32 v34, v33
	s_nop 0
	v_fma_f32 v35, -v33, v34, 1.0
	v_fmac_f32_e32 v34, v35, v34
	v_div_scale_f32 v35, vcc, 1.0, v32, 1.0
	v_mul_f32_e32 v36, v35, v34
	v_fma_f32 v37, -v33, v36, v35
	v_fmac_f32_e32 v36, v37, v34
	v_fma_f32 v33, -v33, v36, v35
	v_div_fmas_f32 v33, v33, v34, v36
	v_div_fixup_f32 v34, v33, v32, 1.0
	v_pk_mul_f32 v[16:17], v[16:17], v[34:35] op_sel_hi:[1,0]
	v_pk_mul_f32 v[18:19], v[18:19], v[34:35] op_sel_hi:[1,0]
	v_mul_f32_e32 v32, v17, v17
	v_fmac_f32_e32 v32, v16, v16
	v_fmac_f32_e32 v32, v18, v18
	v_pk_mul_f32 v[20:21], v[20:21], v[34:35] op_sel_hi:[1,0]
	v_fmac_f32_e32 v32, v19, v19
	v_fmac_f32_e32 v32, v20, v20
	v_pk_mul_f32 v[22:23], v[22:23], v[34:35] op_sel_hi:[1,0]
	v_fmac_f32_e32 v32, v21, v21
	v_fmac_f32_e32 v32, v22, v22
	v_pk_mul_f32 v[24:25], v[24:25], v[34:35] op_sel_hi:[1,0]
	v_fmac_f32_e32 v32, v23, v23
	v_fmac_f32_e32 v32, v24, v24
	v_pk_mul_f32 v[26:27], v[26:27], v[34:35] op_sel_hi:[1,0]
	v_fmac_f32_e32 v32, v25, v25
	v_fmac_f32_e32 v32, v26, v26
	v_pk_mul_f32 v[28:29], v[28:29], v[34:35] op_sel_hi:[1,0]
	v_fmac_f32_e32 v32, v27, v27
	v_fmac_f32_e32 v32, v28, v28
	v_pk_mul_f32 v[30:31], v[30:31], v[34:35] op_sel_hi:[1,0]
	v_fmac_f32_e32 v32, v29, v29
	v_fmac_f32_e32 v32, v30, v30
	v_fmac_f32_e32 v32, v31, v31
	v_pk_mul_f32 v[0:1], v[0:1], v[34:35] op_sel_hi:[1,0]
	v_pk_mul_f32 v[2:3], v[2:3], v[34:35] op_sel_hi:[1,0]
	v_fmac_f32_e32 v32, v0, v0
	v_fmac_f32_e32 v32, v1, v1
	v_fmac_f32_e32 v32, v2, v2
	v_pk_mul_f32 v[4:5], v[4:5], v[34:35] op_sel_hi:[1,0]
	v_fmac_f32_e32 v32, v3, v3
	v_fmac_f32_e32 v32, v4, v4
	v_pk_mul_f32 v[6:7], v[6:7], v[34:35] op_sel_hi:[1,0]
	v_fmac_f32_e32 v32, v5, v5
	v_fmac_f32_e32 v32, v6, v6
	v_pk_mul_f32 v[8:9], v[8:9], v[34:35] op_sel_hi:[1,0]
	v_fmac_f32_e32 v32, v7, v7
	v_fmac_f32_e32 v32, v8, v8
	v_pk_mul_f32 v[10:11], v[10:11], v[34:35] op_sel_hi:[1,0]
	v_fmac_f32_e32 v32, v9, v9
	v_fmac_f32_e32 v32, v10, v10
	v_pk_mul_f32 v[12:13], v[12:13], v[34:35] op_sel_hi:[1,0]
	v_fmac_f32_e32 v32, v11, v11
	v_fmac_f32_e32 v32, v12, v12
	v_pk_mul_f32 v[14:15], v[14:15], v[34:35] op_sel_hi:[1,0]
	v_fmac_f32_e32 v32, v13, v13
	v_fmac_f32_e32 v32, v14, v14
	v_fmac_f32_e32 v32, v15, v15
	v_mov_b32_e32 v33, v32
	s_nop 1
	v_permlane32_swap_b32_e32 v32, v33
	s_and_saveexec_b64 s[42:43], s[0:1]
	v_add_f32_e32 v32, v32, v33
	ds_write_b32 v72, v32 offset:128
	s_or_b64 exec, exec, s[42:43]
	v_lshlrev_b64 v[36:37], 1, v[184:185]
	v_lshl_add_u64 v[32:33], s[72:73], 0, v[188:189]
	v_lshlrev_b32_e32 v178, 1, v186
	v_lshl_add_u64 v[32:33], v[32:33], 0, v[36:37]
	v_lshl_add_u64 v[32:33], v[32:33], 0, v[178:179]
	v_add_co_u32_e32 v34, vcc, s46, v32
	s_waitcnt lgkmcnt(0)
	s_nop 0
	v_addc_co_u32_e32 v35, vcc, 0, v33, vcc
	s_barrier
	v_lshl_add_u32 v72, v200, 2, 0
	ds_read2st64_b32 v[34:35], v72 offset1:1
	ds_read2st64_b32 v[50:51], v72 offset0:2 offset1:3
	ds_read2st64_b32 v[78:79], v72 offset0:4 offset1:5
	ds_read2st64_b32 v[80:81], v72 offset0:6 offset1:7
	v_mov_b32_e32 v82, v65
	s_waitcnt lgkmcnt(3)
	v_add_f32_e32 v34, 0, v34
	v_add_f32_e32 v34, v34, v35
	s_waitcnt lgkmcnt(2)
	v_add_f32_e32 v34, v34, v50
	v_add_f32_e32 v34, v34, v51
	s_waitcnt lgkmcnt(1)
	v_add_f32_e32 v34, v34, v78
	v_add_f32_e32 v34, v34, v79
	s_waitcnt lgkmcnt(0)
	v_add_f32_e32 v34, v34, v80
	v_add_f32_e32 v34, v34, v81
	v_fmamk_f32 v34, v34, 0x3b000000, v196
	v_mul_f32_e32 v35, 0x4b800000, v34
	v_cmp_gt_f32_e32 vcc, s35, v34
	v_mov_b32_e32 v78, v67
	v_mov_b32_e32 v80, v64
	v_cndmask_b32_e32 v34, v34, v35, vcc
	v_lshl_add_u64 v[36:37], s[20:21], 0, v[36:37]
	s_waitcnt vmcnt(2)
	v_lshl_add_u32 v164, v180, 3, s66
	s_mov_b32 s8, 0
	s_mov_b64 s[0:1], -1
	s_waitcnt vmcnt(0)
	v_mov_b64_e32 v[74:75], v[124:125]
	v_mov_b64_e32 v[76:77], v[126:127]
	v_mov_b32_e32 v73, v76
	s_nop 1
	v_permlane32_swap_b32_e32 v74, v73
	v_lshlrev_b32_e32 v51, 16, v74
	v_mul_f32_e32 v50, 0xbfb8aa3b, v51
	v_exp_f32_e32 v50, v50
	v_rsq_f32_e32 v76, v34
	v_mov_b32_e32 v83, v77
	s_nop 1
	v_permlane32_swap_b32_e32 v75, v83
	v_add_f32_e32 v34, 1.0, v50
	v_rcp_f32_e32 v35, v34
	v_mul_f32_e32 v50, 0x45800000, v76
	v_mov_b32_e32 v34, v70
	v_cndmask_b32_e32 v50, v76, v50, vcc
	v_pk_mul_f32 v[34:35], v[34:35], v[50:51]
	v_and_b32_e32 v51, 0xffff0000, v74
	v_mul_f32_e32 v70, 0xbfb8aa3b, v51
	v_exp_f32_e32 v74, v70
	v_mov_b32_e32 v70, v71
	v_mov_b32_e32 v76, v68
	v_mul_f32_e32 v34, v34, v35
	v_add_f32_e32 v71, 1.0, v74
	v_rcp_f32_e32 v71, v71
	s_nop 0
	v_pk_mul_f32 v[70:71], v[70:71], v[50:51]
	v_lshlrev_b32_e32 v51, 16, v75
	v_mul_f32_e32 v74, 0xbfb8aa3b, v51
	v_exp_f32_e32 v74, v74
	s_nop 0
	v_add_f32_e32 v74, 1.0, v74
	v_rcp_f32_e32 v77, v74
	v_mov_b32_e32 v74, v69
	v_pk_mul_f32 v[76:77], v[76:77], v[50:51]
	v_and_b32_e32 v51, 0xffff0000, v75
	v_mul_f32_e32 v68, 0xbfb8aa3b, v51
	v_exp_f32_e32 v68, v68
	v_mul_f32_e32 v67, v76, v77
	v_add_f32_e32 v68, 1.0, v68
	v_rcp_f32_e32 v75, v68
	s_nop 0
	v_pk_mul_f32 v[68:69], v[74:75], v[50:51]
	v_lshlrev_b32_e32 v51, 16, v73
	v_mul_f32_e32 v74, 0xbfb8aa3b, v51
	v_exp_f32_e32 v74, v74
	v_mul_f32_e32 v68, v68, v69
	v_add_f32_e32 v74, 1.0, v74
	v_rcp_f32_e32 v75, v74
	v_mov_b32_e32 v74, v66
	v_pk_mul_f32 v[74:75], v[74:75], v[50:51]
	v_and_b32_e32 v51, 0xffff0000, v73
	v_mul_f32_e32 v66, 0xbfb8aa3b, v51
	v_exp_f32_e32 v66, v66
	s_nop 0
	v_add_f32_e32 v66, 1.0, v66
	v_rcp_f32_e32 v79, v66
	s_nop 0
	v_pk_mul_f32 v[78:79], v[78:79], v[50:51]
	v_lshlrev_b32_e32 v51, 16, v83
	v_mul_f32_e32 v64, 0xbfb8aa3b, v51
	v_exp_f32_e32 v66, v64
	v_lshl_add_u64 v[64:65], v[32:33], 0, s[6:7]
	v_add_f32_e32 v35, 1.0, v66
	v_rcp_f32_e32 v81, v35
	v_mul_f32_e32 v35, v70, v71
	v_cvt_pk_bf16_f32 v66, v34, v35
	v_cvt_pk_bf16_f32 v67, v67, v68
	v_pk_mul_f32 v[34:35], v[80:81], v[50:51]
	v_and_b32_e32 v51, 0xffff0000, v83
	v_mul_f32_e32 v70, 0xbfb8aa3b, v51
	v_exp_f32_e32 v70, v70
	v_mul_f32_e32 v68, v74, v75
	v_mov_b32_e32 v80, v63
	v_add_f32_e32 v69, 1.0, v70
	v_rcp_f32_e32 v83, v69
	v_mul_f32_e32 v69, v78, v79
	v_cvt_pk_bf16_f32 v68, v68, v69
	v_mul_f32_e32 v69, v34, v35
	v_pk_mul_f32 v[34:35], v[82:83], v[50:51]
	v_permlane32_swap_b32_e32 v66, v68
	v_mul_f32_e32 v34, v34, v35
	v_cvt_pk_bf16_f32 v69, v69, v34
	v_mov_b64_e32 v[74:75], v[128:129]
	v_mov_b64_e32 v[76:77], v[130:131]
	v_permlane32_swap_b32_e32 v67, v69
	v_mov_b32_e32 v73, v76
	s_nop 1
	v_permlane32_swap_b32_e32 v74, v73
	v_lshlrev_b32_e32 v51, 16, v74
	v_mul_f32_e32 v34, 0xbfb8aa3b, v51
	v_exp_f32_e32 v34, v34
	v_mov_b32_e32 v81, v77
	s_nop 1
	v_permlane32_swap_b32_e32 v75, v81
	v_add_f32_e32 v34, 1.0, v34
	v_rcp_f32_e32 v35, v34
	v_mov_b32_e32 v34, v56
	v_pk_mul_f32 v[70:71], v[34:35], v[50:51]
	v_and_b32_e32 v51, 0xffff0000, v74
	v_mul_f32_e32 v34, 0xbfb8aa3b, v51
	v_exp_f32_e32 v35, v34
	v_mov_b32_e32 v34, v57
	v_add_f32_e32 v35, 1.0, v35
	v_rcp_f32_e32 v35, v35
	s_nop 0
	v_pk_mul_f32 v[76:77], v[34:35], v[50:51]
	v_lshlrev_b32_e32 v51, 16, v75
	v_mul_f32_e32 v34, 0xbfb8aa3b, v51
	v_exp_f32_e32 v34, v34
	s_nop 0
	v_add_f32_e32 v34, 1.0, v34
	v_rcp_f32_e32 v35, v34
	v_mov_b32_e32 v34, v58
	v_mov_b32_e32 v58, v61
	v_pk_mul_f32 v[78:79], v[34:35], v[50:51]
	v_and_b32_e32 v51, 0xffff0000, v75
	v_mul_f32_e32 v34, 0xbfb8aa3b, v51
	v_exp_f32_e32 v34, v34
	s_nop 0
	v_add_f32_e32 v34, 1.0, v34
	v_rcp_f32_e32 v35, v34
	v_mov_b32_e32 v34, v59
	v_pk_mul_f32 v[74:75], v[34:35], v[50:51]
	v_lshlrev_b32_e32 v51, 16, v73
	v_mul_f32_e32 v34, 0xbfb8aa3b, v51
	v_exp_f32_e32 v56, v34
	v_lshlrev_b64 v[34:35], 11, v[182:183]
	v_add_f32_e32 v56, 1.0, v56
	v_rcp_f32_e32 v57, v56
	v_mov_b32_e32 v56, v60
	v_pk_mul_f32 v[60:61], v[56:57], v[50:51]
	v_and_b32_e32 v51, 0xffff0000, v73
	v_mul_f32_e32 v56, 0xbfb8aa3b, v51
	v_exp_f32_e32 v59, v56
	v_lshl_add_u64 v[56:57], v[36:37], 0, v[34:35]
	v_lshl_add_u64 v[56:57], v[56:57], 0, v[178:179]
	global_store_dwordx4 v[56:57], v[66:69], off
	v_add_f32_e32 v59, 1.0, v59
	v_rcp_f32_e32 v59, v59
	v_mul_f32_e32 v60, v60, v61
	v_mul_f32_e32 v67, v74, v75
	v_mov_b32_e32 v74, v39
	v_pk_mul_f32 v[82:83], v[58:59], v[50:51]
	v_lshlrev_b32_e32 v51, 16, v81
	v_mul_f32_e32 v58, 0xbfb8aa3b, v51
	v_exp_f32_e32 v58, v58
	v_mul_f32_e32 v59, v70, v71
	v_or_b32_e32 v34, 0x10000, v34
	v_add_f32_e32 v58, 1.0, v58
	v_rcp_f32_e32 v63, v58
	v_mul_f32_e32 v58, v76, v77
	v_cvt_pk_bf16_f32 v58, v59, v58
	v_mul_f32_e32 v59, v78, v79
	v_pk_mul_f32 v[62:63], v[62:63], v[50:51]
	v_and_b32_e32 v51, 0xffff0000, v81
	v_mul_f32_e32 v66, 0xbfb8aa3b, v51
	v_exp_f32_e32 v66, v66
	v_cvt_pk_bf16_f32 v59, v59, v67
	s_nop 0
	v_add_f32_e32 v61, 1.0, v66
	v_rcp_f32_e32 v81, v61
	v_mul_f32_e32 v61, v82, v83
	v_cvt_pk_bf16_f32 v60, v60, v61
	v_mul_f32_e32 v61, v62, v63
	v_pk_mul_f32 v[62:63], v[80:81], v[50:51]
	v_permlane32_swap_b32_e32 v58, v60
	v_mul_f32_e32 v51, v62, v63
	v_cvt_pk_bf16_f32 v61, v61, v51
	v_mov_b64_e32 v[66:67], v[132:133]
	v_mov_b64_e32 v[68:69], v[134:135]
	v_permlane32_swap_b32_e32 v59, v61
	global_store_dwordx4 v[56:57], v[58:61], off offset:32
	v_mov_b32_e32 v73, v68
	s_nop 1
	v_permlane32_swap_b32_e32 v66, v73
	v_lshlrev_b32_e32 v51, 16, v66
	v_mul_f32_e32 v62, 0xbfb8aa3b, v51
	v_exp_f32_e32 v62, v62
	v_mov_b32_e32 v75, v69
	s_nop 1
	v_permlane32_swap_b32_e32 v67, v75
	v_add_f32_e32 v62, 1.0, v62
	v_rcp_f32_e32 v63, v62
	v_mov_b32_e32 v62, v54
	v_mov_b32_e32 v68, v52
	v_pk_mul_f32 v[62:63], v[62:63], v[50:51]
	v_and_b32_e32 v51, 0xffff0000, v66
	v_mul_f32_e32 v54, 0xbfb8aa3b, v51
	v_exp_f32_e32 v66, v54
	v_mov_b32_e32 v54, v55
	v_add_f32_e32 v55, 1.0, v66
	v_rcp_f32_e32 v55, v55
	s_nop 0
	v_pk_mul_f32 v[54:55], v[54:55], v[50:51]
	v_lshlrev_b32_e32 v51, 16, v67
	v_mul_f32_e32 v66, 0xbfb8aa3b, v51
	v_exp_f32_e32 v66, v66
	s_nop 0
	v_add_f32_e32 v66, 1.0, v66
	v_rcp_f32_e32 v69, v66
	v_mov_b32_e32 v66, v53
	v_pk_mul_f32 v[68:69], v[68:69], v[50:51]
	v_and_b32_e32 v51, 0xffff0000, v67
	v_mul_f32_e32 v52, 0xbfb8aa3b, v51
	v_exp_f32_e32 v52, v52
	s_nop 0
	v_add_f32_e32 v52, 1.0, v52
	v_rcp_f32_e32 v67, v52
	s_nop 0
	v_pk_mul_f32 v[66:67], v[66:67], v[50:51]
	v_lshlrev_b32_e32 v51, 16, v73
	v_mul_f32_e32 v52, 0xbfb8aa3b, v51
	v_exp_f32_e32 v52, v52
	s_nop 0
	v_add_f32_e32 v52, 1.0, v52
	v_rcp_f32_e32 v53, v52
	v_mov_b32_e32 v52, v48
	v_pk_mul_f32 v[70:71], v[52:53], v[50:51]
	v_and_b32_e32 v51, 0xffff0000, v73
	v_mul_f32_e32 v48, 0xbfb8aa3b, v51
	v_exp_f32_e32 v52, v48
	v_mov_b32_e32 v48, v49
	v_mul_f32_e32 v53, v54, v55
	v_mul_f32_e32 v55, v66, v67
	v_add_f32_e32 v49, 1.0, v52
	v_rcp_f32_e32 v49, v49
	v_mul_f32_e32 v52, v62, v63
	v_cvt_pk_bf16_f32 v52, v52, v53
	v_mul_f32_e32 v53, v68, v69
	v_pk_mul_f32 v[48:49], v[48:49], v[50:51]
	v_lshlrev_b32_e32 v51, 16, v75
	v_mul_f32_e32 v39, 0xbfb8aa3b, v51
	v_exp_f32_e32 v39, v39
	v_mul_f32_e32 v48, v48, v49
	v_cvt_pk_bf16_f32 v53, v53, v55
	v_mul_f32_e32 v55, v70, v71
	v_add_f32_e32 v39, 1.0, v39
	v_rcp_f32_e32 v39, v39
	s_nop 0
	v_pk_mul_f32 v[38:39], v[38:39], v[50:51]
	v_and_b32_e32 v51, 0xffff0000, v75
	v_mul_f32_e32 v54, 0xbfb8aa3b, v51
	v_exp_f32_e32 v54, v54
	s_nop 0
	v_add_f32_e32 v54, 1.0, v54
	v_rcp_f32_e32 v75, v54
	v_cvt_pk_bf16_f32 v54, v55, v48
	v_mul_f32_e32 v48, v38, v39
	v_permlane32_swap_b32_e32 v52, v54
	v_pk_mul_f32 v[38:39], v[74:75], v[50:51]
	s_nop 0
	v_mul_f32_e32 v38, v38, v39
	v_cvt_pk_bf16_f32 v55, v48, v38
	v_mov_b64_e32 v[58:59], v[136:137]
	v_mov_b64_e32 v[60:61], v[138:139]
	v_permlane32_swap_b32_e32 v53, v55
	global_store_dwordx4 v[56:57], v[52:55], off offset:64
	v_permlane32_swap_b32_e32 v58, v60
	v_lshlrev_b32_e32 v51, 16, v58
	v_mul_f32_e32 v38, 0xbfb8aa3b, v51
	v_exp_f32_e32 v38, v38
	v_permlane32_swap_b32_e32 v59, v61
	v_add_u32_e32 v52, 0x80, v72
	v_add_f32_e32 v38, 1.0, v38
	v_rcp_f32_e32 v39, v38
	v_mov_b32_e32 v38, v40
	v_pk_mul_f32 v[38:39], v[38:39], v[50:51]
	v_and_b32_e32 v51, 0xffff0000, v58
	v_mul_f32_e32 v40, 0xbfb8aa3b, v51
	v_exp_f32_e32 v48, v40
	v_mov_b32_e32 v40, v41
	v_mov_b32_e32 v58, v43
	v_mul_f32_e32 v38, v38, v39
	v_add_f32_e32 v41, 1.0, v48
	v_rcp_f32_e32 v41, v41
	s_nop 0
	v_pk_mul_f32 v[40:41], v[40:41], v[50:51]
	v_lshlrev_b32_e32 v51, 16, v59
	v_mul_f32_e32 v48, 0xbfb8aa3b, v51
	v_exp_f32_e32 v48, v48
	s_nop 0
	v_add_f32_e32 v48, 1.0, v48
	v_rcp_f32_e32 v49, v48
	v_mov_b32_e32 v48, v42
	v_pk_mul_f32 v[48:49], v[48:49], v[50:51]
	v_and_b32_e32 v51, 0xffff0000, v59
	v_mul_f32_e32 v42, 0xbfb8aa3b, v51
	v_exp_f32_e32 v42, v42
	s_nop 0
	v_add_f32_e32 v42, 1.0, v42
	v_rcp_f32_e32 v59, v42
	s_nop 0
	v_pk_mul_f32 v[42:43], v[58:59], v[50:51]
	v_lshlrev_b32_e32 v51, 16, v60
	v_mul_f32_e32 v58, 0xbfb8aa3b, v51
	v_exp_f32_e32 v58, v58
	v_mul_f32_e32 v42, v42, v43
	v_add_f32_e32 v58, 1.0, v58
	v_rcp_f32_e32 v59, v58
	v_mov_b32_e32 v58, v44
	v_pk_mul_f32 v[58:59], v[58:59], v[50:51]
	v_and_b32_e32 v51, 0xffff0000, v60
	v_mul_f32_e32 v44, 0xbfb8aa3b, v51
	v_exp_f32_e32 v62, v44
	v_mov_b32_e32 v44, v45
	v_mov_b32_e32 v60, v47
	v_add_f32_e32 v45, 1.0, v62
	v_rcp_f32_e32 v45, v45
	v_add_co_u32_e32 v62, vcc, s47, v32
	v_pk_mul_f32 v[44:45], v[44:45], v[50:51]
	v_lshlrev_b32_e32 v51, 16, v61
	v_mul_f32_e32 v47, 0xbfb8aa3b, v51
	v_exp_f32_e32 v47, v47
	v_addc_co_u32_e32 v63, vcc, 0, v33, vcc
	v_add_f32_e32 v39, 1.0, v47
	v_rcp_f32_e32 v47, v39
	v_mul_f32_e32 v39, v40, v41
	v_cvt_pk_bf16_f32 v40, v38, v39
	v_mul_f32_e32 v41, v48, v49
	v_pk_mul_f32 v[38:39], v[46:47], v[50:51]
	v_and_b32_e32 v51, 0xffff0000, v61
	v_mul_f32_e32 v46, 0xbfb8aa3b, v51
	v_exp_f32_e32 v46, v46
	v_cvt_pk_bf16_f32 v41, v41, v42
	v_mul_f32_e32 v42, v58, v59
	v_add_f32_e32 v43, 1.0, v46
	v_rcp_f32_e32 v61, v43
	v_mul_f32_e32 v43, v44, v45
	v_cvt_pk_bf16_f32 v42, v42, v43
	v_mul_f32_e32 v43, v38, v39
	v_pk_mul_f32 v[38:39], v[60:61], v[50:51]
	v_permlane32_swap_b32_e32 v40, v42
	v_mul_f32_e32 v38, v38, v39
	v_cvt_pk_bf16_f32 v43, v43, v38
	v_mov_b64_e32 v[44:45], v[140:141]
	v_mov_b64_e32 v[46:47], v[142:143]
	ds_read2_b32 v[38:39], v72 offset0:32 offset1:96
	ds_read2_b32 v[48:49], v72 offset0:160 offset1:224
	ds_read2st64_b32 v[50:51], v52 offset0:4 offset1:5
	ds_read2st64_b32 v[52:53], v52 offset0:6 offset1:7
	v_permlane32_swap_b32_e32 v41, v43
	global_store_dwordx4 v[56:57], v[40:43], off offset:96
	s_waitcnt lgkmcnt(3)
	v_add_f32_e32 v38, 0, v38
	v_add_f32_e32 v38, v38, v39
	s_waitcnt lgkmcnt(2)
	v_add_f32_e32 v38, v38, v48
	v_add_f32_e32 v38, v38, v49
	s_waitcnt lgkmcnt(1)
	v_add_f32_e32 v38, v38, v50
	v_add_f32_e32 v38, v38, v51
	s_waitcnt lgkmcnt(0)
	v_add_f32_e32 v38, v38, v52
	v_add_f32_e32 v38, v38, v53
	v_fmamk_f32 v38, v38, 0x3b000000, v196
	v_mul_f32_e32 v48, 0x4b800000, v38
	v_cmp_gt_f32_e32 vcc, s35, v38
	v_mov_b32_e32 v52, v46
	s_nop 1
	v_permlane32_swap_b32_e32 v44, v52
	v_lshlrev_b32_e32 v39, 16, v44
	v_mul_f32_e32 v46, 0xbfb8aa3b, v39
	v_exp_f32_e32 v46, v46
	v_cndmask_b32_e32 v38, v38, v48, vcc
	v_rsq_f32_e32 v38, v38
	v_mov_b32_e32 v48, v16
	v_add_f32_e32 v46, 1.0, v46
	v_rcp_f32_e32 v49, v46
	v_mul_f32_e32 v16, 0x45800000, v38
	v_cndmask_b32_e32 v38, v38, v16, vcc
	v_mov_b32_e32 v53, v47
	v_pk_mul_f32 v[48:49], v[48:49], v[38:39]
	v_and_b32_e32 v39, 0xffff0000, v44
	v_mul_f32_e32 v16, 0xbfb8aa3b, v39
	v_exp_f32_e32 v44, v16
	v_mov_b32_e32 v16, v17
	v_permlane32_swap_b32_e32 v45, v53
	v_add_f32_e32 v17, 1.0, v44
	v_rcp_f32_e32 v17, v17
	v_mov_b32_e32 v46, v18
	v_pk_mul_f32 v[16:17], v[16:17], v[38:39]
	v_lshlrev_b32_e32 v39, 16, v45
	v_mul_f32_e32 v44, 0xbfb8aa3b, v39
	v_exp_f32_e32 v44, v44
	v_mul_f32_e32 v16, v16, v17
	v_add_f32_e32 v44, 1.0, v44
	v_rcp_f32_e32 v47, v44
	v_mov_b32_e32 v44, v19
	v_pk_mul_f32 v[46:47], v[46:47], v[38:39]
	v_and_b32_e32 v39, 0xffff0000, v45
	v_mul_f32_e32 v18, 0xbfb8aa3b, v39
	v_exp_f32_e32 v18, v18
	s_nop 0
	v_add_f32_e32 v18, 1.0, v18
	v_rcp_f32_e32 v45, v18
	s_nop 0
	v_pk_mul_f32 v[44:45], v[44:45], v[38:39]
	v_lshlrev_b32_e32 v39, 16, v52
	v_mul_f32_e32 v18, 0xbfb8aa3b, v39
	v_exp_f32_e32 v18, v18
	s_nop 0
	v_add_f32_e32 v18, 1.0, v18
	v_rcp_f32_e32 v19, v18
	v_mov_b32_e32 v18, v20
	v_mov_b32_e32 v20, v21
	v_pk_mul_f32 v[50:51], v[18:19], v[38:39]
	v_and_b32_e32 v39, 0xffff0000, v52
	v_mul_f32_e32 v18, 0xbfb8aa3b, v39
	v_exp_f32_e32 v18, v18
	v_mov_b32_e32 v52, v23
	v_add_f32_e32 v18, 1.0, v18
	v_rcp_f32_e32 v21, v18
	v_lshl_add_u64 v[18:19], v[32:33], 0, s[12:13]
	v_pk_mul_f32 v[32:33], v[20:21], v[38:39]
	v_lshlrev_b32_e32 v39, 16, v53
	v_mul_f32_e32 v20, 0xbfb8aa3b, v39
	v_exp_f32_e32 v20, v20
	v_mul_f32_e32 v21, v48, v49
	v_add_f32_e32 v20, 1.0, v20
	v_rcp_f32_e32 v23, v20
	v_cvt_pk_bf16_f32 v20, v21, v16
	v_mul_f32_e32 v21, v46, v47
	v_pk_mul_f32 v[16:17], v[22:23], v[38:39]
	v_and_b32_e32 v39, 0xffff0000, v53
	v_mul_f32_e32 v22, 0xbfb8aa3b, v39
	v_exp_f32_e32 v22, v22
	v_mul_f32_e32 v23, v44, v45
	v_cvt_pk_bf16_f32 v21, v21, v23
	v_mul_f32_e32 v23, v50, v51
	v_add_f32_e32 v22, 1.0, v22
	v_rcp_f32_e32 v53, v22
	v_mul_f32_e32 v22, v32, v33
	v_cvt_pk_bf16_f32 v22, v23, v22
	v_mul_f32_e32 v23, v16, v17
	v_pk_mul_f32 v[16:17], v[52:53], v[38:39]
	v_permlane32_swap_b32_e32 v20, v22
	v_mul_f32_e32 v16, v16, v17
	v_cvt_pk_bf16_f32 v23, v23, v16
	v_mov_b64_e32 v[40:41], v[144:145]
	v_mov_b64_e32 v[42:43], v[146:147]
	v_permlane32_swap_b32_e32 v21, v23
	v_mov_b32_e32 v44, v42
	s_nop 1
	v_permlane32_swap_b32_e32 v40, v44
	v_lshlrev_b32_e32 v39, 16, v40
	v_mul_f32_e32 v16, 0xbfb8aa3b, v39
	v_exp_f32_e32 v16, v16
	v_mov_b32_e32 v45, v43
	s_nop 1
	v_permlane32_swap_b32_e32 v41, v45
	v_add_f32_e32 v16, 1.0, v16
	v_rcp_f32_e32 v17, v16
	v_mov_b32_e32 v16, v24
	v_pk_mul_f32 v[32:33], v[16:17], v[38:39]
	v_and_b32_e32 v39, 0xffff0000, v40
	v_mul_f32_e32 v16, 0xbfb8aa3b, v39
	v_exp_f32_e32 v17, v16
	v_mov_b32_e32 v16, v25
	v_add_f32_e32 v17, 1.0, v17
	v_rcp_f32_e32 v17, v17
	s_nop 0
	v_pk_mul_f32 v[24:25], v[16:17], v[38:39]
	v_lshlrev_b32_e32 v39, 16, v41
	v_mul_f32_e32 v16, 0xbfb8aa3b, v39
	v_exp_f32_e32 v16, v16
	s_nop 0
	v_add_f32_e32 v16, 1.0, v16
	v_rcp_f32_e32 v17, v16
	v_mov_b32_e32 v16, v26
	v_pk_mul_f32 v[42:43], v[16:17], v[38:39]
	v_and_b32_e32 v39, 0xffff0000, v41
	v_mul_f32_e32 v16, 0xbfb8aa3b, v39
	v_exp_f32_e32 v16, v16
	s_nop 0
	v_add_f32_e32 v16, 1.0, v16
	v_rcp_f32_e32 v17, v16
	v_mov_b32_e32 v16, v27
	v_pk_mul_f32 v[26:27], v[16:17], v[38:39]
	v_lshlrev_b32_e32 v39, 16, v44
	v_mul_f32_e32 v16, 0xbfb8aa3b, v39
	v_exp_f32_e32 v16, v16
	s_nop 0
	v_add_f32_e32 v16, 1.0, v16
	v_rcp_f32_e32 v17, v16
	v_mov_b32_e32 v16, v28
	v_mov_b32_e32 v28, v29
	v_pk_mul_f32 v[40:41], v[16:17], v[38:39]
	v_and_b32_e32 v39, 0xffff0000, v44
	v_mul_f32_e32 v16, 0xbfb8aa3b, v39
	v_exp_f32_e32 v29, v16
	v_mov_b32_e32 v44, v31
	v_lshl_add_u64 v[16:17], v[36:37], 0, v[34:35]
	v_lshl_add_u64 v[16:17], v[16:17], 0, v[178:179]
	v_add_f32_e32 v29, 1.0, v29
	v_rcp_f32_e32 v29, v29
	global_store_dwordx4 v[16:17], v[20:23], off
	v_lshlrev_b32_e32 v178, 5, v199
	v_pk_mul_f32 v[28:29], v[28:29], v[38:39]
	v_lshlrev_b32_e32 v39, 16, v45
	v_mul_f32_e32 v31, 0xbfb8aa3b, v39
	v_exp_f32_e32 v31, v31
	v_mul_f32_e32 v20, v32, v33
	v_mul_f32_e32 v23, v26, v27
	v_add_f32_e32 v21, 1.0, v31
	v_rcp_f32_e32 v31, v21
	v_mul_f32_e32 v21, v24, v25
	v_cvt_pk_bf16_f32 v20, v20, v21
	v_mul_f32_e32 v21, v42, v43
	v_pk_mul_f32 v[24:25], v[30:31], v[38:39]
	v_and_b32_e32 v39, 0xffff0000, v45
	v_mul_f32_e32 v22, 0xbfb8aa3b, v39
	v_exp_f32_e32 v22, v22
	v_cvt_pk_bf16_f32 v21, v21, v23
	v_mul_f32_e32 v23, v40, v41
	v_add_f32_e32 v22, 1.0, v22
	v_rcp_f32_e32 v45, v22
	v_mul_f32_e32 v22, v28, v29
	v_cvt_pk_bf16_f32 v22, v23, v22
	v_mul_f32_e32 v23, v24, v25
	v_pk_mul_f32 v[24:25], v[44:45], v[38:39]
	v_mov_b32_e32 v28, v0
	v_mul_f32_e32 v24, v24, v25
	v_cvt_pk_bf16_f32 v23, v23, v24
	v_mov_b64_e32 v[24:25], v[148:149]
	v_mov_b64_e32 v[26:27], v[150:151]
	v_permlane32_swap_b32_e32 v20, v22
	v_permlane32_swap_b32_e32 v21, v23
	global_store_dwordx4 v[16:17], v[20:23], off offset:32
	v_mov_b32_e32 v30, v26
	s_nop 1
	v_permlane32_swap_b32_e32 v24, v30
	v_lshlrev_b32_e32 v39, 16, v24
	v_mul_f32_e32 v26, 0xbfb8aa3b, v39
	v_exp_f32_e32 v26, v26
	v_mov_b32_e32 v31, v27
	s_nop 1
	v_permlane32_swap_b32_e32 v25, v31
	v_add_f32_e32 v26, 1.0, v26
	v_rcp_f32_e32 v29, v26
	v_mov_b32_e32 v26, v2
	v_lshl_add_u64 v[22:23], s[60:61], 0, v[178:179]
	v_pk_mul_f32 v[28:29], v[28:29], v[38:39]
	v_and_b32_e32 v39, 0xffff0000, v24
	v_mul_f32_e32 v0, 0xbfb8aa3b, v39
	v_exp_f32_e32 v24, v0
	v_mov_b32_e32 v0, v1
	v_mul_f32_e32 v20, v28, v29
	v_add_f32_e32 v1, 1.0, v24
	v_rcp_f32_e32 v1, v1
	s_nop 0
	v_pk_mul_f32 v[0:1], v[0:1], v[38:39]
	v_lshlrev_b32_e32 v39, 16, v25
	v_mul_f32_e32 v24, 0xbfb8aa3b, v39
	v_exp_f32_e32 v24, v24
	v_mul_f32_e32 v0, v0, v1
	v_cvt_pk_bf16_f32 v0, v20, v0
	v_add_f32_e32 v24, 1.0, v24
	v_rcp_f32_e32 v27, v24
	v_mov_b32_e32 v24, v3
	v_pk_mul_f32 v[26:27], v[26:27], v[38:39]
	v_and_b32_e32 v39, 0xffff0000, v25
	v_mul_f32_e32 v2, 0xbfb8aa3b, v39
	v_exp_f32_e32 v2, v2
	v_mul_f32_e32 v1, v26, v27
	v_add_f32_e32 v2, 1.0, v2
	v_rcp_f32_e32 v25, v2
	s_nop 0
	v_pk_mul_f32 v[2:3], v[24:25], v[38:39]
	v_lshlrev_b32_e32 v39, 16, v30
	v_mul_f32_e32 v24, 0xbfb8aa3b, v39
	v_exp_f32_e32 v24, v24
	v_mul_f32_e32 v2, v2, v3
	v_cvt_pk_bf16_f32 v1, v1, v2
	v_add_f32_e32 v24, 1.0, v24
	v_rcp_f32_e32 v25, v24
	v_mov_b32_e32 v24, v4
	v_pk_mul_f32 v[24:25], v[24:25], v[38:39]
	v_and_b32_e32 v39, 0xffff0000, v30
	v_mul_f32_e32 v4, 0xbfb8aa3b, v39
	v_exp_f32_e32 v30, v4
	v_mov_b32_e32 v4, v5
	v_mul_f32_e32 v2, v24, v25
	v_lshl_add_u64 v[24:25], v[22:23], 0, s[36:37]
	v_add_f32_e32 v5, 1.0, v30
	v_rcp_f32_e32 v5, v5
	v_mov_b32_e32 v30, v7
	v_pk_mul_f32 v[4:5], v[4:5], v[38:39]
	v_lshlrev_b32_e32 v39, 16, v31
	v_mul_f32_e32 v7, 0xbfb8aa3b, v39
	v_exp_f32_e32 v7, v7
	s_nop 0
	v_add_f32_e32 v7, 1.0, v7
	v_rcp_f32_e32 v7, v7
	s_nop 0
	v_pk_mul_f32 v[6:7], v[6:7], v[38:39]
	v_and_b32_e32 v39, 0xffff0000, v31
	v_mul_f32_e32 v20, 0xbfb8aa3b, v39
	v_exp_f32_e32 v20, v20
	s_nop 0
	v_add_f32_e32 v3, 1.0, v20
	v_rcp_f32_e32 v31, v3
	v_mul_f32_e32 v3, v4, v5
	v_cvt_pk_bf16_f32 v2, v2, v3
	v_mul_f32_e32 v3, v6, v7
	v_pk_mul_f32 v[4:5], v[30:31], v[38:39]
	v_permlane32_swap_b32_e32 v0, v2
	v_mul_f32_e32 v4, v4, v5
	v_cvt_pk_bf16_f32 v3, v3, v4
	v_mov_b64_e32 v[4:5], v[152:153]
	v_mov_b64_e32 v[6:7], v[154:155]
	v_mov_b32_e32 v18, v8
	v_mov_b32_e32 v8, v9
	v_permlane32_swap_b32_e32 v1, v3
	global_store_dwordx4 v[16:17], v[0:3], off offset:64
	v_mov_b32_e32 v20, v15
	v_mov_b32_e32 v21, v6
	s_nop 1
	v_permlane32_swap_b32_e32 v4, v21
	v_lshlrev_b32_e32 v39, 16, v4
	v_mul_f32_e32 v6, 0xbfb8aa3b, v39
	v_exp_f32_e32 v6, v6
	v_mov_b32_e32 v26, v7
	s_nop 1
	v_permlane32_swap_b32_e32 v5, v26
	v_add_f32_e32 v6, 1.0, v6
	v_rcp_f32_e32 v19, v6
	s_nop 0
	v_pk_mul_f32 v[18:19], v[18:19], v[38:39]
	v_and_b32_e32 v39, 0xffff0000, v4
	v_mul_f32_e32 v4, 0xbfb8aa3b, v39
	v_exp_f32_e32 v4, v4
	s_nop 0
	v_add_f32_e32 v4, 1.0, v4
	v_rcp_f32_e32 v9, v4
	s_nop 0
	v_pk_mul_f32 v[6:7], v[8:9], v[38:39]
	v_lshlrev_b32_e32 v39, 16, v5
	v_mul_f32_e32 v4, 0xbfb8aa3b, v39
	v_exp_f32_e32 v4, v4
	v_mov_b32_e32 v8, v10
	v_mul_f32_e32 v6, v6, v7
	v_add_f32_e32 v4, 1.0, v4
	v_rcp_f32_e32 v9, v4
	s_nop 0
	v_pk_mul_f32 v[8:9], v[8:9], v[38:39]
	v_and_b32_e32 v39, 0xffff0000, v5
	v_mul_f32_e32 v4, 0xbfb8aa3b, v39
	v_exp_f32_e32 v4, v4
	s_nop 0
	v_add_f32_e32 v4, 1.0, v4
	v_rcp_f32_e32 v5, v4
	v_mov_b32_e32 v4, v11
	v_pk_mul_f32 v[4:5], v[4:5], v[38:39]
	v_lshlrev_b32_e32 v39, 16, v21
	v_mul_f32_e32 v10, 0xbfb8aa3b, v39
	v_exp_f32_e32 v11, v10
	v_mov_b32_e32 v10, v13
	v_mul_f32_e32 v4, v4, v5
	v_add_f32_e32 v11, 1.0, v11
	v_rcp_f32_e32 v13, v11
	s_nop 0
	v_pk_mul_f32 v[12:13], v[12:13], v[38:39]
	v_and_b32_e32 v39, 0xffff0000, v21
	v_mul_f32_e32 v11, 0xbfb8aa3b, v39
	v_exp_f32_e32 v11, v11
	v_mul_f32_e32 v7, v12, v13
	v_add_co_u32_e32 v12, vcc, s46, v22
	v_add_f32_e32 v11, 1.0, v11
	v_rcp_f32_e32 v11, v11
	v_addc_co_u32_e32 v13, vcc, 0, v23, vcc
	v_cmp_gt_u32_e32 vcc, s46, v164
	v_pk_mul_f32 v[2:3], v[10:11], v[38:39]
	v_lshlrev_b32_e32 v39, 16, v26
	v_mul_f32_e32 v0, 0xbfb8aa3b, v39
	v_exp_f32_e32 v1, v0
	v_mul_f32_e32 v0, v18, v19
	v_cvt_pk_bf16_f32 v0, v0, v6
	v_mul_f32_e32 v2, v2, v3
	v_add_f32_e32 v1, 1.0, v1
	v_rcp_f32_e32 v15, v1
	v_mul_f32_e32 v1, v8, v9
	v_cvt_pk_bf16_f32 v1, v1, v4
	v_cvt_pk_bf16_f32 v2, v7, v2
	v_pk_mul_f32 v[4:5], v[14:15], v[38:39]
	v_and_b32_e32 v39, 0xffff0000, v26
	v_mul_f32_e32 v6, 0xbfb8aa3b, v39
	v_exp_f32_e32 v6, v6
	v_permlane32_swap_b32_e32 v0, v2
	v_cndmask_b32_e64 v65, 0, 1.0, vcc
	v_add_f32_e32 v3, 1.0, v6
	v_rcp_f32_e32 v21, v3
	v_mul_f32_e32 v3, v4, v5
	v_mov_b32_e32 v66, v65
	v_mov_b32_e32 v68, v65
	v_pk_mul_f32 v[4:5], v[20:21], v[38:39]
	v_mov_b32_e32 v69, v65
	v_mul_f32_e32 v4, v4, v5
	v_cvt_pk_bf16_f32 v3, v3, v4
	s_nop 0
	v_permlane32_swap_b32_e32 v1, v3
	global_store_dwordx4 v[16:17], v[0:3], off offset:96
	s_bitcmp1_b32 s3, 3
	s_cbranch_scc0 .Lb_conv
	s_mov_b32 s98, 0
	s_branch .Lb_adv
